# U hidden activations stored in LDS-image order: contiguous 1KB epilogue stores in up-GEMM, linear LDS-DMA staging in down-GEMM
# baseline (speedup 1.0000x reference)
.LBB0_1764:
	s_lshl_b32 s15, s58, 8
	s_lshl_b32 s17, s57, 8
	s_add_i32 s15, s15, s52
	s_or_b32 s17, s17, s53
	s_ashr_i32 s22, s17, 6
	s_ashr_i32 s24, s15, 8
	s_ashr_i32 s23, s22, 31
	s_ashr_i32 s25, s24, 31
	s_lshl_b64 s[24:25], s[24:25], 22
	s_lshl_b64 s[22:23], s[22:23], 15
	v_or_b32_e32 v152, s15, v1
	s_add_u32 s15, s10, s24
	s_addc_u32 s17, s11, s25
	s_add_u32 s24, s15, s22
	v_lshlrev_b32_e32 v18, 7, v152
	v_max_f32_e32 v124, v124, v124
	s_addc_u32 s25, s17, s23
	v_and_b32_e32 v18, 0x6780, v18
	v_max_f32_e32 v124, 0, v124
	v_lshl_add_u64 v[150:151], s[24:25], 0, v[18:19]
	s_lshl_b32 s100, s52, 7
	s_bfe_u32 s101, s53, 0x10005
	s_lshl_b32 s101, s101, 10
	s_add_i32 s100, s100, s101
	s_add_u32 s24, s24, s100
	s_addc_u32 s25, s25, 0
	s_add_u32 s100, s24, 0x10000
	s_addc_u32 s101, s25, 0
	v_mbcnt_lo_u32_b32 v232, -1, 0
	v_mbcnt_hi_u32_b32 v232, -1, v232
	v_and_b32_e32 v233, 15, v232
	v_lshrrev_b32_e32 v234, 4, v232
	v_lshrrev_b32_e32 v235, 2, v233
	v_and_b32_e32 v235, 2, v235
	v_xor_b32_e32 v234, v234, v235
	v_lshlrev_b32_e32 v234, 4, v234
	v_lshl_or_b32 v232, v233, 6, v234
	v_max_f32_e32 v18, v128, v128
	v_mul_f32_e32 v128, v124, v124
	v_max_f32_e32 v124, v129, v129
	v_max_f32_e32 v18, 0, v18
	v_max_f32_e32 v124, 0, v124
	v_max_f32_e32 v125, v125, v125
	v_max_f32_e32 v126, v126, v126
	v_max_f32_e32 v116, v116, v116
	v_max_f32_e32 v117, v117, v117
	v_max_f32_e32 v118, v118, v118
	v_mul_f32_e32 v18, v18, v18
	v_max_f32_e32 v125, 0, v125
	v_mul_f32_e32 v124, v124, v124
	v_max_f32_e32 v126, 0, v126
	v_max_f32_e32 v116, 0, v116
	v_max_f32_e32 v117, 0, v117
	v_max_f32_e32 v118, 0, v118
	v_mul_f32_e32 v129, v125, v125
	v_max_f32_e32 v125, v130, v130
	v_mul_f32_e32 v130, v126, v126
	v_max_f32_e32 v126, v131, v131
	v_max_f32_e32 v127, v127, v127
	v_cvt_pk_bf16_f32 v124, v18, v124
	v_max_f32_e32 v18, v120, v120
	v_mul_f32_e32 v120, v116, v116
	v_max_f32_e32 v116, v121, v121
	v_mul_f32_e32 v121, v117, v117
	v_max_f32_e32 v117, v122, v122
	v_mul_f32_e32 v122, v118, v118
	v_max_f32_e32 v118, v123, v123
	v_mov_b32_e32 v145, v19
	v_max_f32_e32 v125, 0, v125
	v_max_f32_e32 v126, 0, v126
	v_max_f32_e32 v127, 0, v127
	v_max_f32_e32 v116, 0, v116
	v_max_f32_e32 v117, 0, v117
	v_max_f32_e32 v118, 0, v118
	v_lshl_add_u64 v[150:151], v[150:151], 0, v[144:145]
	v_mul_f32_e32 v125, v125, v125
	v_mul_f32_e32 v126, v126, v126
	v_mul_f32_e32 v127, v127, v127
	v_max_f32_e32 v18, 0, v18
	v_mul_f32_e32 v116, v116, v116
	v_mul_f32_e32 v117, v117, v117
	v_max_f32_e32 v119, v119, v119
	v_mul_f32_e32 v118, v118, v118
	s_mov_b32 s17, 0x10000
	v_max_f32_e32 v108, v108, v108
	v_cvt_pk_bf16_f32 v125, v125, v126
	v_cvt_pk_bf16_f32 v126, v128, v129
	v_cvt_pk_bf16_f32 v127, v130, v127
	global_store_dwordx4 v232, v[124:127], s[24:25]
	v_mul_f32_e32 v18, v18, v18
	v_max_f32_e32 v119, 0, v119
	v_cvt_pk_bf16_f32 v116, v18, v116
	v_cvt_pk_bf16_f32 v117, v117, v118
	v_cvt_pk_bf16_f32 v118, v120, v121
	v_add_co_u32_e32 v120, vcc, s17, v150
	v_max_f32_e32 v108, 0, v108
	v_mul_f32_e32 v119, v119, v119
	v_addc_co_u32_e32 v121, vcc, 0, v151, vcc
	s_mov_b32 s15, 0x11000
	v_max_f32_e32 v18, v112, v112
	v_mul_f32_e32 v112, v108, v108
	v_max_f32_e32 v108, v113, v113
	v_cvt_pk_bf16_f32 v119, v122, v119
	v_add_co_u32_e32 v122, vcc, s15, v150
	v_max_f32_e32 v18, 0, v18
	v_max_f32_e32 v108, 0, v108
	v_max_f32_e32 v109, v109, v109
	v_max_f32_e32 v110, v110, v110
	v_max_f32_e32 v100, v100, v100
	v_addc_co_u32_e32 v123, vcc, 0, v151, vcc
	v_mul_f32_e32 v18, v18, v18
	v_max_f32_e32 v109, 0, v109
	v_mul_f32_e32 v108, v108, v108
	v_max_f32_e32 v110, 0, v110
	v_max_f32_e32 v100, 0, v100
	global_store_dwordx4 v232, v[116:119], s[100:101]
	v_mul_f32_e32 v113, v109, v109
	v_max_f32_e32 v109, v114, v114
	v_mul_f32_e32 v114, v110, v110
	v_max_f32_e32 v110, v115, v115
	v_max_f32_e32 v111, v111, v111
	v_cvt_pk_bf16_f32 v108, v18, v108
	v_max_f32_e32 v18, v104, v104
	v_mul_f32_e32 v104, v100, v100
	v_max_f32_e32 v100, v105, v105
	v_max_f32_e32 v109, 0, v109
	v_max_f32_e32 v110, 0, v110
	v_max_f32_e32 v111, 0, v111
	v_max_f32_e32 v18, 0, v18
	v_max_f32_e32 v100, 0, v100
	v_max_f32_e32 v101, v101, v101
	v_max_f32_e32 v102, v102, v102
	v_max_f32_e32 v92, v92, v92
	v_mul_f32_e32 v109, v109, v109
	v_mul_f32_e32 v110, v110, v110
	v_mul_f32_e32 v111, v111, v111
	v_mul_f32_e32 v18, v18, v18
	v_max_f32_e32 v101, 0, v101
	v_mul_f32_e32 v100, v100, v100
	v_max_f32_e32 v102, 0, v102
	v_max_f32_e32 v92, 0, v92
	v_max_f32_e32 v93, v93, v93
	v_max_f32_e32 v94, v94, v94
	v_cvt_pk_bf16_f32 v109, v109, v110
	v_cvt_pk_bf16_f32 v110, v112, v113
	v_cvt_pk_bf16_f32 v111, v114, v111
	global_store_dwordx4 v232, v[108:111], s[24:25] offset:2048
	v_mul_f32_e32 v105, v101, v101
	v_max_f32_e32 v101, v106, v106
	v_mul_f32_e32 v106, v102, v102
	v_max_f32_e32 v102, v107, v107
	v_max_f32_e32 v103, v103, v103
	v_cvt_pk_bf16_f32 v100, v18, v100
	v_max_f32_e32 v18, v96, v96
	v_mul_f32_e32 v96, v92, v92
	v_max_f32_e32 v92, v97, v97
	v_max_f32_e32 v93, 0, v93
	v_max_f32_e32 v94, 0, v94
	v_max_f32_e32 v101, 0, v101
	v_max_f32_e32 v102, 0, v102
	v_max_f32_e32 v103, 0, v103
	v_max_f32_e32 v18, 0, v18
	v_max_f32_e32 v92, 0, v92
	v_mul_f32_e32 v97, v93, v93
	v_max_f32_e32 v93, v98, v98
	v_mul_f32_e32 v98, v94, v94
	v_max_f32_e32 v94, v99, v99
	v_max_f32_e32 v84, v84, v84
	v_mul_f32_e32 v101, v101, v101
	v_mul_f32_e32 v102, v102, v102
	v_mul_f32_e32 v103, v103, v103
	v_mul_f32_e32 v18, v18, v18
	v_mul_f32_e32 v92, v92, v92
	v_max_f32_e32 v93, 0, v93
	v_max_f32_e32 v94, 0, v94
	v_max_f32_e32 v84, 0, v84
	v_cvt_pk_bf16_f32 v101, v101, v102
	v_cvt_pk_bf16_f32 v102, v104, v105
	v_cvt_pk_bf16_f32 v103, v106, v103
	global_store_dwordx4 v232, v[100:103], s[100:101] offset:2048
	v_mul_f32_e32 v93, v93, v93
	v_max_f32_e32 v95, v95, v95
	v_mul_f32_e32 v94, v94, v94
	v_cvt_pk_bf16_f32 v92, v18, v92
	v_max_f32_e32 v18, v88, v88
	v_mul_f32_e32 v88, v84, v84
	v_max_f32_e32 v84, v89, v89
	v_max_f32_e32 v95, 0, v95
	v_cvt_pk_bf16_f32 v93, v93, v94
	v_cvt_pk_bf16_f32 v94, v96, v97
	v_add_co_u32_e32 v96, vcc, s3, v150
	v_max_f32_e32 v18, 0, v18
	v_max_f32_e32 v84, 0, v84
	v_max_f32_e32 v85, v85, v85
	v_max_f32_e32 v86, v86, v86
	v_max_f32_e32 v76, v76, v76
	v_mul_f32_e32 v95, v95, v95
	v_addc_co_u32_e32 v97, vcc, 0, v151, vcc
	v_mul_f32_e32 v18, v18, v18
	v_max_f32_e32 v85, 0, v85
	v_mul_f32_e32 v84, v84, v84
	v_max_f32_e32 v86, 0, v86
	v_max_f32_e32 v76, 0, v76
	v_cvt_pk_bf16_f32 v95, v98, v95
	s_add_u32 s24, s24, 0x1000
	s_addc_u32 s25, s25, 0
	s_add_u32 s100, s100, 0x1000
	s_addc_u32 s101, s101, 0
	global_store_dwordx4 v232, v[92:95], s[24:25]
	v_mul_f32_e32 v89, v85, v85
	v_max_f32_e32 v85, v90, v90
	v_mul_f32_e32 v90, v86, v86
	v_max_f32_e32 v86, v91, v91
	v_max_f32_e32 v87, v87, v87
	v_cvt_pk_bf16_f32 v84, v18, v84
	v_max_f32_e32 v18, v80, v80
	v_mul_f32_e32 v80, v76, v76
	v_max_f32_e32 v76, v81, v81
	v_max_f32_e32 v85, 0, v85
	v_max_f32_e32 v86, 0, v86
	v_max_f32_e32 v87, 0, v87
	v_max_f32_e32 v18, 0, v18
	v_max_f32_e32 v76, 0, v76
	v_max_f32_e32 v77, v77, v77
	v_max_f32_e32 v78, v78, v78
	v_max_f32_e32 v68, v68, v68
	v_mul_f32_e32 v85, v85, v85
	v_mul_f32_e32 v86, v86, v86
	v_mul_f32_e32 v87, v87, v87
	v_mul_f32_e32 v18, v18, v18
	v_max_f32_e32 v77, 0, v77
	v_mul_f32_e32 v76, v76, v76
	v_max_f32_e32 v78, 0, v78
	v_max_f32_e32 v68, 0, v68
	v_max_f32_e32 v69, v69, v69
	v_max_f32_e32 v70, v70, v70
	v_cvt_pk_bf16_f32 v85, v85, v86
	v_cvt_pk_bf16_f32 v86, v88, v89
	v_cvt_pk_bf16_f32 v87, v90, v87
	global_store_dwordx4 v232, v[84:87], s[100:101]
	v_mul_f32_e32 v81, v77, v77
	v_max_f32_e32 v77, v82, v82
	v_mul_f32_e32 v82, v78, v78
	v_max_f32_e32 v78, v83, v83
	v_max_f32_e32 v79, v79, v79
	v_cvt_pk_bf16_f32 v76, v18, v76
	v_max_f32_e32 v18, v72, v72
	v_mul_f32_e32 v72, v68, v68
	v_max_f32_e32 v68, v73, v73
	v_max_f32_e32 v69, 0, v69
	v_max_f32_e32 v70, 0, v70
	v_max_f32_e32 v77, 0, v77
	v_max_f32_e32 v78, 0, v78
	v_max_f32_e32 v79, 0, v79
	v_max_f32_e32 v18, 0, v18
	v_max_f32_e32 v68, 0, v68
	v_mul_f32_e32 v73, v69, v69
	v_max_f32_e32 v69, v74, v74
	v_mul_f32_e32 v74, v70, v70
	v_max_f32_e32 v70, v75, v75
	v_max_f32_e32 v71, v71, v71
	v_mul_f32_e32 v77, v77, v77
	v_mul_f32_e32 v78, v78, v78
	v_mul_f32_e32 v79, v79, v79
	v_mul_f32_e32 v18, v18, v18
	v_mul_f32_e32 v68, v68, v68
	v_max_f32_e32 v69, 0, v69
	v_max_f32_e32 v70, 0, v70
	v_max_f32_e32 v71, 0, v71
	v_cvt_pk_bf16_f32 v77, v77, v78
	v_cvt_pk_bf16_f32 v78, v80, v81
	v_cvt_pk_bf16_f32 v79, v82, v79
	global_store_dwordx4 v232, v[76:79], s[24:25] offset:2048
	v_mul_f32_e32 v69, v69, v69
	v_mul_f32_e32 v70, v70, v70
	v_mul_f32_e32 v71, v71, v71
	v_cvt_pk_bf16_f32 v68, v18, v68
	v_add_u32_e32 v18, 0x80, v152
	v_cvt_pk_bf16_f32 v69, v69, v70
	v_cvt_pk_bf16_f32 v70, v72, v73
	v_cvt_pk_bf16_f32 v71, v74, v71
	global_store_dwordx4 v232, v[68:71], s[100:101] offset:2048
	v_max_f32_e32 v60, v60, v60
	v_max_f32_e32 v60, 0, v60
	v_ashrrev_i32_e32 v68, 8, v18
	v_ashrrev_i32_e32 v69, 31, v68
	v_lshlrev_b64 v[68:69], 22, v[68:69]
	v_lshl_add_u64 v[68:69], s[10:11], 0, v[68:69]
	v_lshlrev_b32_e32 v18, 7, v18
	v_lshl_add_u64 v[68:69], v[68:69], 0, s[22:23]
	v_and_b32_e32 v18, 0x6780, v18
	v_lshl_add_u64 v[70:71], v[68:69], 0, v[18:19]
	v_max_f32_e32 v18, v64, v64
	v_mul_f32_e32 v64, v60, v60
	v_max_f32_e32 v60, v65, v65
	v_max_f32_e32 v18, 0, v18
	v_max_f32_e32 v60, 0, v60
	v_max_f32_e32 v61, v61, v61
	v_max_f32_e32 v62, v62, v62
	v_max_f32_e32 v52, v52, v52
	v_mul_f32_e32 v18, v18, v18
	v_max_f32_e32 v61, 0, v61
	v_mul_f32_e32 v60, v60, v60
	v_max_f32_e32 v62, 0, v62
	v_max_f32_e32 v52, 0, v52
	v_max_f32_e32 v53, v53, v53
	v_max_f32_e32 v54, v54, v54
	v_mul_f32_e32 v65, v61, v61
	v_max_f32_e32 v61, v66, v66
	v_mul_f32_e32 v66, v62, v62
	v_max_f32_e32 v62, v67, v67
	v_max_f32_e32 v63, v63, v63
	v_cvt_pk_bf16_f32 v60, v18, v60
	v_max_f32_e32 v18, v56, v56
	v_mul_f32_e32 v56, v52, v52
	v_max_f32_e32 v52, v57, v57
	v_max_f32_e32 v53, 0, v53
	v_max_f32_e32 v54, 0, v54
	v_max_f32_e32 v61, 0, v61
	v_max_f32_e32 v62, 0, v62
	v_max_f32_e32 v63, 0, v63
	v_max_f32_e32 v18, 0, v18
	v_max_f32_e32 v52, 0, v52
	v_mul_f32_e32 v57, v53, v53
	v_max_f32_e32 v53, v58, v58
	v_mul_f32_e32 v58, v54, v54
	v_max_f32_e32 v54, v59, v59
	v_lshlrev_b32_e32 v149, 6, v152
	v_lshl_add_u64 v[70:71], v[70:71], 0, v[144:145]
	v_mul_f32_e32 v61, v61, v61
	v_mul_f32_e32 v62, v62, v62
	v_mul_f32_e32 v63, v63, v63
	v_mul_f32_e32 v18, v18, v18
	v_mul_f32_e32 v52, v52, v52
	v_max_f32_e32 v53, 0, v53
	v_max_f32_e32 v54, 0, v54
	v_cvt_pk_bf16_f32 v61, v61, v62
	v_cvt_pk_bf16_f32 v62, v64, v65
	v_cvt_pk_bf16_f32 v63, v66, v63
	s_add_u32 s24, s24, 0x3000
	s_addc_u32 s25, s25, 0
	s_add_u32 s100, s100, 0x3000
	s_addc_u32 s101, s101, 0
	global_store_dwordx4 v232, v[60:63], s[24:25]
	v_mul_f32_e32 v53, v53, v53
	v_max_f32_e32 v55, v55, v55
	v_mul_f32_e32 v54, v54, v54
	v_cvt_pk_bf16_f32 v52, v18, v52
	v_add_u32_e32 v18, 0x2400, v149
	v_max_f32_e32 v55, 0, v55
	v_cvt_pk_bf16_f32 v53, v53, v54
	v_cvt_pk_bf16_f32 v54, v56, v57
	v_add_co_u32_e32 v56, vcc, s17, v70
	v_and_b32_e32 v18, 0x37c0, v18
	v_max_f32_e32 v44, v44, v44
	v_mul_f32_e32 v55, v55, v55
	v_addc_co_u32_e32 v57, vcc, 0, v71, vcc
	v_lshlrev_b32_e32 v18, 1, v18
	v_max_f32_e32 v44, 0, v44
	v_cvt_pk_bf16_f32 v55, v58, v55
	global_store_dwordx4 v232, v[52:55], s[100:101]
	v_max_f32_e32 v45, v45, v45
	v_max_f32_e32 v46, v46, v46
	v_lshl_add_u64 v[52:53], v[68:69], 0, v[18:19]
	v_max_f32_e32 v18, v48, v48
	v_mul_f32_e32 v48, v44, v44
	v_max_f32_e32 v44, v49, v49
	v_max_f32_e32 v18, 0, v18
	v_max_f32_e32 v44, 0, v44
	v_max_f32_e32 v36, v36, v36
	v_mul_f32_e32 v18, v18, v18
	v_max_f32_e32 v45, 0, v45
	v_mul_f32_e32 v44, v44, v44
	v_max_f32_e32 v46, 0, v46
	v_max_f32_e32 v36, 0, v36
	v_max_f32_e32 v37, v37, v37
	v_max_f32_e32 v38, v38, v38
	v_mul_f32_e32 v49, v45, v45
	v_max_f32_e32 v45, v50, v50
	v_mul_f32_e32 v50, v46, v46
	v_max_f32_e32 v46, v51, v51
	v_max_f32_e32 v47, v47, v47
	v_cvt_pk_bf16_f32 v44, v18, v44
	v_max_f32_e32 v18, v40, v40
	v_mul_f32_e32 v40, v36, v36
	v_max_f32_e32 v36, v41, v41
	v_max_f32_e32 v37, 0, v37
	v_max_f32_e32 v38, 0, v38
	v_max_f32_e32 v45, 0, v45
	v_max_f32_e32 v46, 0, v46
	v_max_f32_e32 v47, 0, v47
	v_max_f32_e32 v18, 0, v18
	v_max_f32_e32 v36, 0, v36
	v_mul_f32_e32 v41, v37, v37
	v_max_f32_e32 v37, v42, v42
	v_mul_f32_e32 v42, v38, v38
	v_max_f32_e32 v38, v43, v43
	v_lshl_add_u64 v[52:53], v[52:53], 0, v[144:145]
	v_mul_f32_e32 v45, v45, v45
	v_mul_f32_e32 v46, v46, v46
	v_mul_f32_e32 v47, v47, v47
	v_mul_f32_e32 v18, v18, v18
	v_mul_f32_e32 v36, v36, v36
	v_max_f32_e32 v37, 0, v37
	v_max_f32_e32 v38, 0, v38
	v_cvt_pk_bf16_f32 v45, v45, v46
	v_cvt_pk_bf16_f32 v46, v48, v49
	v_cvt_pk_bf16_f32 v47, v50, v47
	global_store_dwordx4 v232, v[44:47], s[24:25] offset:2048
	v_mul_f32_e32 v37, v37, v37
	v_max_f32_e32 v39, v39, v39
	v_mul_f32_e32 v38, v38, v38
	v_cvt_pk_bf16_f32 v36, v18, v36
	v_add_u32_e32 v18, 0x2800, v149
	v_max_f32_e32 v39, 0, v39
	v_cvt_pk_bf16_f32 v37, v37, v38
	v_cvt_pk_bf16_f32 v38, v40, v41
	v_add_co_u32_e32 v40, vcc, s17, v52
	v_and_b32_e32 v18, 0x3bc0, v18
	v_max_f32_e32 v28, v28, v28
	v_mul_f32_e32 v39, v39, v39
	v_addc_co_u32_e32 v41, vcc, 0, v53, vcc
	v_lshlrev_b32_e32 v18, 1, v18
	v_max_f32_e32 v28, 0, v28
	v_cvt_pk_bf16_f32 v39, v42, v39
	global_store_dwordx4 v232, v[36:39], s[100:101] offset:2048
	v_max_f32_e32 v29, v29, v29
	v_max_f32_e32 v30, v30, v30
	v_lshl_add_u64 v[36:37], v[68:69], 0, v[18:19]
	v_max_f32_e32 v18, v32, v32
	v_mul_f32_e32 v32, v28, v28
	v_max_f32_e32 v28, v33, v33
	v_max_f32_e32 v18, 0, v18
	v_max_f32_e32 v28, 0, v28
	v_max_f32_e32 v20, v20, v20
	v_mul_f32_e32 v18, v18, v18
	v_max_f32_e32 v29, 0, v29
	v_mul_f32_e32 v28, v28, v28
	v_max_f32_e32 v30, 0, v30
	v_max_f32_e32 v20, 0, v20
	v_max_f32_e32 v21, v21, v21
	v_max_f32_e32 v22, v22, v22
	v_mul_f32_e32 v33, v29, v29
	v_max_f32_e32 v29, v34, v34
	v_mul_f32_e32 v34, v30, v30
	v_max_f32_e32 v30, v35, v35
	v_max_f32_e32 v31, v31, v31
	v_cvt_pk_bf16_f32 v28, v18, v28
	v_max_f32_e32 v18, v24, v24
	v_mul_f32_e32 v24, v20, v20
	v_max_f32_e32 v20, v25, v25
	v_max_f32_e32 v21, 0, v21
	v_max_f32_e32 v22, 0, v22
	v_max_f32_e32 v29, 0, v29
	v_max_f32_e32 v30, 0, v30
	v_max_f32_e32 v31, 0, v31
	v_max_f32_e32 v18, 0, v18
	v_max_f32_e32 v20, 0, v20
	v_mul_f32_e32 v25, v21, v21
	v_max_f32_e32 v21, v26, v26
	v_mul_f32_e32 v26, v22, v22
	v_max_f32_e32 v22, v27, v27
	v_lshl_add_u64 v[36:37], v[36:37], 0, v[144:145]
	v_mul_f32_e32 v29, v29, v29
	v_mul_f32_e32 v30, v30, v30
	v_mul_f32_e32 v31, v31, v31
	v_mul_f32_e32 v18, v18, v18
	v_mul_f32_e32 v20, v20, v20
	v_max_f32_e32 v21, 0, v21
	v_max_f32_e32 v22, 0, v22
	v_cvt_pk_bf16_f32 v29, v29, v30
	v_cvt_pk_bf16_f32 v30, v32, v33
	v_cvt_pk_bf16_f32 v31, v34, v31
	s_add_u32 s24, s24, 0x1000
	s_addc_u32 s25, s25, 0
	s_add_u32 s100, s100, 0x1000
	s_addc_u32 s101, s101, 0
	global_store_dwordx4 v232, v[28:31], s[24:25]
	v_mul_f32_e32 v21, v21, v21
	v_max_f32_e32 v23, v23, v23
	v_mul_f32_e32 v22, v22, v22
	v_cvt_pk_bf16_f32 v20, v18, v20
	v_add_u32_e32 v18, 0x2c00, v149
	v_max_f32_e32 v23, 0, v23
	v_cvt_pk_bf16_f32 v21, v21, v22
	v_cvt_pk_bf16_f32 v22, v24, v25
	v_add_co_u32_e32 v24, vcc, s17, v36
	v_and_b32_e32 v18, 0x3fc0, v18
	v_max_f32_e32 v10, v10, v10
	v_mul_f32_e32 v23, v23, v23
	v_addc_co_u32_e32 v25, vcc, 0, v37, vcc
	v_lshlrev_b32_e32 v18, 1, v18
	v_max_f32_e32 v10, 0, v10
	v_max_f32_e32 v11, v11, v11
	v_max_f32_e32 v12, v12, v12
	v_cvt_pk_bf16_f32 v23, v26, v23
	global_store_dwordx4 v232, v[20:23], s[100:101]
	v_max_f32_e32 v11, 0, v11
	v_max_f32_e32 v12, 0, v12
	v_lshl_add_u64 v[20:21], v[68:69], 0, v[18:19]
	v_mul_f32_e32 v18, v10, v10
	v_max_f32_e32 v10, v15, v15
	v_max_f32_e32 v14, v14, v14
	v_max_f32_e32 v10, 0, v10
	v_mul_f32_e32 v15, v11, v11
	v_max_f32_e32 v11, v16, v16
	v_mul_f32_e32 v16, v12, v12
	v_max_f32_e32 v12, v17, v17
	v_max_f32_e32 v13, v13, v13
	v_max_f32_e32 v14, 0, v14
	v_mul_f32_e32 v10, v10, v10
	v_max_f32_e32 v11, 0, v11
	v_max_f32_e32 v12, 0, v12
	v_max_f32_e32 v13, 0, v13
	v_max_f32_e32 v2, v2, v2
	v_lshl_add_u64 v[20:21], v[20:21], 0, v[144:145]
	v_mul_f32_e32 v14, v14, v14
	v_mul_f32_e32 v11, v11, v11
	v_mul_f32_e32 v12, v12, v12
	v_mul_f32_e32 v13, v13, v13
	v_cvt_pk_bf16_f32 v10, v14, v10
	v_max_f32_e32 v2, 0, v2
	v_max_f32_e32 v3, v3, v3
	v_max_f32_e32 v4, v4, v4
	v_cvt_pk_bf16_f32 v11, v11, v12
	v_cvt_pk_bf16_f32 v12, v18, v15
	v_cvt_pk_bf16_f32 v13, v16, v13
	global_store_dwordx4 v232, v[10:13], s[24:25] offset:2048
	v_max_f32_e32 v6, v6, v6
	v_max_f32_e32 v3, 0, v3
	v_mul_f32_e32 v10, v2, v2
	v_max_f32_e32 v2, v7, v7
	v_max_f32_e32 v4, 0, v4
	v_max_f32_e32 v6, 0, v6
	v_max_f32_e32 v2, 0, v2
	v_mul_f32_e32 v7, v3, v3
	v_max_f32_e32 v3, v8, v8
	v_mul_f32_e32 v8, v4, v4
	v_max_f32_e32 v4, v9, v9
	v_mul_f32_e32 v6, v6, v6
	v_mul_f32_e32 v2, v2, v2
	v_max_f32_e32 v3, 0, v3
	v_max_f32_e32 v4, 0, v4
	v_mul_f32_e32 v3, v3, v3
	v_max_f32_e32 v5, v5, v5
	v_mul_f32_e32 v4, v4, v4
	v_cvt_pk_bf16_f32 v2, v6, v2
	v_add_co_u32_e32 v6, vcc, 0x10000, v20
	v_max_f32_e32 v5, 0, v5
	v_cvt_pk_bf16_f32 v3, v3, v4
	v_cvt_pk_bf16_f32 v4, v10, v7
	s_nop 0
	v_addc_co_u32_e32 v7, vcc, 0, v21, vcc
	v_readlane_b32 s62, v250, 20
	v_mul_f32_e32 v5, v5, v5
	s_andn2_b64 vcc, exec, s[0:1]
	s_mov_b64 s[0:1], -1
	s_mov_b32 s60, s68
	v_readlane_b32 s63, v250, 21
	v_cvt_pk_bf16_f32 v5, v8, v5
	global_store_dwordx4 v232, v[2:5], s[100:101] offset:2048
	s_cbranch_vccnz .LBB0_1757
	s_andn2_b64 vcc, exec, s[8:9]
	s_cbranch_vccnz .LBB0_1756
	s_barrier
	s_branch .LBB0_1756

.LBB0_1842:
	v_bfe_i32 v4, v2, 27, 1
	v_lshlrev_b32_e32 v1, 4, v2
	v_lshrrev_b32_e32 v4, 22, v4
	v_ashrrev_i32_e32 v3, 31, v2
	v_add_u32_e32 v4, v1, v4
	v_lshrrev_b32_e32 v3, 26, v3
	v_and_b32_e32 v4, 0xfffffc00, v4
	v_add_u32_e32 v3, v2, v3
	v_sub_u32_e32 v4, v1, v4
	v_ashrrev_i32_e32 v3, 6, v3
	v_lshrrev_b32_e32 v5, 4, v4
	v_bitop3_b32 v5, v5, v4, 32 bitop3:0x6c
	v_lshlrev_b32_e32 v4, 3, v3
	s_waitcnt lgkmcnt(4)
	v_and_b32_e32 v6, -16, v4
	v_ashrrev_i32_e32 v4, 31, v5
	v_lshrrev_b32_e32 v4, 26, v4
	v_add_u32_e32 v7, v5, v4
	s_add_u32 s42, s8, 0x37300000
	s_mov_b32 s89, s91
	v_ashrrev_i32_e32 v4, 6, v7
	v_and_b32_e32 v7, 0xc0, v7
	s_addc_u32 s43, s9, 0
	s_lshl_b64 s[8:9], s[88:89], 25
	v_sub_u32_e32 v5, v5, v7
	s_add_u32 s6, s6, s8
	s_waitcnt lgkmcnt(2)
	v_lshlrev_b32_e32 v8, 5, v3
	v_ashrrev_i16_sdwa v5, v210, sext(v5) dst_sel:DWORD dst_unused:UNUSED_PAD src0_sel:DWORD src1_sel:BYTE_0
	s_addc_u32 s7, s7, s9
	v_and_b32_e32 v8, 32, v8
	v_bfe_i32 v5, v5, 0, 16
	s_add_u32 s44, s6, 0x3f900000
	v_add_u32_e32 v6, v4, v6
	v_and_b32_e32 v10, 3, v4
	s_mov_b32 s6, 0x1ffffe0
	v_add_lshl_u32 v8, v8, v5, 1
	v_add_u32_e32 v1, 0x2000, v1
	v_lshlrev_b32_e32 v7, 1, v6
	v_lshrrev_b32_e32 v9, 2, v6
	v_and_or_b32 v10, v6, s6, v10
	v_lshlrev_b32_e32 v148, 4, v2
	v_ashrrev_i32_e32 v6, 31, v1
	v_lshrrev_b32_e32 v6, 22, v6
	v_and_b32_e32 v7, 24, v7
	v_and_b32_e32 v9, 4, v9
	v_add_u32_e32 v6, v1, v6
	v_or3_b32 v7, v10, v9, v7
	v_ashrrev_i32_e32 v6, 10, v6
	v_lshl_add_u32 v18, v7, 7, v8
	v_mul_i32_i24_e32 v7, 0x400, v6
	v_sub_u32_e32 v1, v1, v7
	v_lshrrev_b32_e32 v7, 4, v1
	v_bitop3_b32 v1, v7, v1, 32 bitop3:0x6c
	v_lshlrev_b32_e32 v7, 3, v6
	v_and_b32_e32 v8, -16, v7
	v_ashrrev_i32_e32 v7, 31, v1
	v_lshrrev_b32_e32 v7, 26, v7
	v_add_u32_e32 v9, v1, v7
	v_ashrrev_i32_e32 v7, 6, v9
	s_addc_u32 s45, s7, 0
	v_add_u32_e32 v10, v7, v8
	s_waitcnt lgkmcnt(0)
	v_and_b32_e32 v12, 3, v7
	s_ashr_i32 s14, s12, 6
	s_ashr_i32 s21, s20, 31
	s_ashr_i32 s23, s22, 31
	s_ashr_i32 s13, s12, 8
	v_and_or_b32 v12, v10, s6, v12
	s_lshl_b32 s46, s14, 10
	s_lshl_b64 s[6:7], s[20:21], 22
	s_lshl_b32 s10, s58, 9
	s_lshl_b64 s[8:9], s[22:23], 22
	s_add_u32 s8, s44, s8
	v_lshlrev_b32_e32 v8, 5, v6
	s_addc_u32 s9, s45, s9
	v_and_b32_e32 v11, 32, v8
	v_and_b32_e32 v8, 0xc0, v9
	s_add_u32 s24, s8, s10
	v_sub_u32_e32 v1, v1, v8
	s_addc_u32 s25, s9, 0
	s_add_i32 s21, s46, 0
	v_ashrrev_i16_sdwa v1, v210, sext(v1) dst_sel:DWORD dst_unused:UNUSED_PAD src0_sel:DWORD src1_sel:BYTE_0
	s_add_i32 m0, s21, 0x10000
	v_bfe_i32 v8, v1, 0, 16
	v_lshlrev_b32_e32 v1, 1, v10
	v_lshrrev_b32_e32 v9, 2, v10
	global_load_lds_dwordx4 v18, s[24:25]
	s_add_i32 m0, s21, 0x12000
	v_and_b32_e32 v1, 24, v1
	v_and_b32_e32 v9, 4, v9
	s_add_u32 s8, s42, s6
	v_or3_b32 v1, v12, v9, v1
	v_add_lshl_u32 v9, v11, v8, 1
	s_addc_u32 s9, s43, s7
	v_lshl_add_u32 v152, v1, 7, v9
	s_add_u32 s6, s24, 0x4000
	global_load_lds_dwordx4 v152, s[24:25]
	s_addc_u32 s7, s25, 0
	s_add_i32 m0, s21, 0x14000
	v_add_u32_e32 v150, 0x2000, v148
	global_load_lds_dwordx4 v18, s[6:7]
	s_add_i32 m0, s21, 0x16000
	s_add_u32 s26, s8, s10
	s_addc_u32 s27, s9, 0
	s_add_i32 s47, s21, 0x2000
	global_load_lds_dwordx4 v152, s[6:7]
	s_mov_b32 m0, s21
	s_add_u32 s6, s26, 0x4000
	global_load_lds_dwordx4 v148, s[26:27]
	s_mov_b32 m0, s47
	s_addc_u32 s7, s27, 0
	s_add_i32 s48, s21, 0x4000
	global_load_lds_dwordx4 v150, s[26:27]
	s_mov_b32 m0, s48
	s_add_i32 s49, s21, 0x6000
	global_load_lds_dwordx4 v148, s[6:7]
	s_mov_b32 m0, s49
	s_cmp_eq_u32 s13, 1
	global_load_lds_dwordx4 v150, s[6:7]
	s_cselect_b64 s[6:7], -1, 0
	s_cmp_lg_u32 s13, 1
	s_cbranch_scc1 .LBB0_1844
	s_barrier
.LBB0_1844:
	s_mul_i32 s9, s88, 0x198000
	s_mul_hi_u32 s8, s88, 0x198000
	s_add_u32 s0, s0, s9
	s_addc_u32 s1, s1, s8
	s_add_u32 s8, s0, 0x10a000
	s_addc_u32 s9, s1, 0
	s_add_u32 s10, s4, 0x31200000
	s_addc_u32 s11, s5, 0
	s_lshl_b32 s0, s14, 5
	s_and_b32 s5, s0, 0x60
	s_lshl_b32 s4, s13, 13
	s_lshl_b32 s14, s5, 7
	s_add_u32 s0, s24, 0x8000
	s_addc_u32 s1, s25, 0
	s_add_i32 m0, s21, 0x18000
	v_lshl_add_u64 v[10:11], s[0:1], 0, v[18:19]
	v_mov_b32_e32 v153, v19
	s_waitcnt vmcnt(2)
	s_barrier
	global_load_lds_dwordx4 v[10:11], off
	s_add_i32 m0, s21, 0x1a000
	v_lshl_add_u64 v[10:11], s[0:1], 0, v[152:153]
	s_add_u32 s0, s26, 0x8000
	v_mov_b32_e32 v149, v19
	s_addc_u32 s1, s27, 0
	s_add_i32 s50, s21, 0x8000
	v_mov_b32_e32 v151, v19
	global_load_lds_dwordx4 v[10:11], off
	v_lshl_add_u64 v[10:11], s[0:1], 0, v[148:149]
	s_mov_b32 m0, s50
	s_add_i32 s51, s21, 0xa000
	global_load_lds_dwordx4 v[10:11], off
	v_lshl_add_u64 v[10:11], s[0:1], 0, v[150:151]
	s_add_u32 s0, s24, 0xc000
	s_mov_b32 m0, s51
	s_addc_u32 s1, s25, 0
	global_load_lds_dwordx4 v[10:11], off
	s_add_i32 m0, s21, 0x1c000
	v_lshl_add_u64 v[10:11], s[0:1], 0, v[18:19]
	global_load_lds_dwordx4 v[10:11], off
	v_lshl_add_u64 v[10:11], s[0:1], 0, v[152:153]
	s_add_i32 m0, s21, 0x1e000
	v_and_b32_e32 v9, 15, v2
	global_load_lds_dwordx4 v[10:11], off
	v_lshrrev_b32_e32 v10, 1, v2
	v_and_b32_e32 v10, 24, v10
	v_lshlrev_b32_e32 v11, 1, v10
	v_lshlrev_b32_e32 v2, 2, v2
	v_lshl_or_b32 v1, s13, 6, v9
	v_lshl_or_b32 v9, v9, 6, v11
	v_and_b32_e32 v2, 32, v2
	v_bitop3_b32 v11, v9, s4, v2 bitop3:0xde
	v_bitop3_b32 v167, v9, s14, v2 bitop3:0xde
	v_lshlrev_b32_e32 v2, 10, v6
	v_and_b32_e32 v2, 0xfffff800, v2
	v_lshl_add_u32 v2, v7, 7, v2
	v_and_b32_e32 v6, 1, v6
	v_lshl_or_b32 v2, v6, 6, v2
	v_mov_b32_e32 v154, v150
	v_lshlrev_b32_e32 v2, 10, v3
	v_and_b32_e32 v2, 0xfffff800, v2
	s_waitcnt vmcnt(6)
	v_lshl_add_u32 v2, v4, 7, v2
	v_and_b32_e32 v3, 1, v3
	s_cmpk_lt_u32 s12, 0x100
	v_lshl_or_b32 v2, v3, 6, v2
	s_cselect_b64 s[12:13], -1, 0
	v_or_b32_e32 v174, s5, v10
	v_mov_b32_e32 v155, v19
	v_mov_b32_e32 v156, v148
	v_mov_b32_e32 v157, v19
	s_mov_b32 s52, 0
	v_add_u32_e32 v175, 0, v11
	s_barrier
	s_branch .LBB0_1847

	.amdhsa_kernel _Z9hymba_fwd4Args
		.amdhsa_group_segment_fixed_size 0
		.amdhsa_private_segment_fixed_size 0
		.amdhsa_kernarg_size 528
		.amdhsa_user_sgpr_count 2
		.amdhsa_user_sgpr_dispatch_ptr 0
		.amdhsa_user_sgpr_queue_ptr 0
		.amdhsa_user_sgpr_kernarg_segment_ptr 1
		.amdhsa_user_sgpr_dispatch_id 0
		.amdhsa_user_sgpr_kernarg_preload_length 0
		.amdhsa_user_sgpr_kernarg_preload_offset 0
		.amdhsa_user_sgpr_private_segment_size 0
		.amdhsa_uses_dynamic_stack 0
		.amdhsa_enable_private_segment 0
		.amdhsa_system_sgpr_workgroup_id_x 1
		.amdhsa_system_sgpr_workgroup_id_y 0
		.amdhsa_system_sgpr_workgroup_id_z 0
		.amdhsa_system_sgpr_workgroup_info 0
		.amdhsa_system_vgpr_workitem_id 0
		.amdhsa_next_free_vgpr 256
		.amdhsa_next_free_sgpr 102
		.amdhsa_accum_offset 256
		.amdhsa_reserve_vcc 1
		.amdhsa_float_round_mode_32 0
		.amdhsa_float_round_mode_16_64 0
		.amdhsa_float_denorm_mode_32 3
		.amdhsa_float_denorm_mode_16_64 3
		.amdhsa_dx10_clamp 1
		.amdhsa_ieee_mode 1
		.amdhsa_fp16_overflow 0
		.amdhsa_tg_split 0
		.amdhsa_exception_fp_ieee_invalid_op 0
		.amdhsa_exception_fp_denorm_src 0
		.amdhsa_exception_fp_ieee_div_zero 0
		.amdhsa_exception_fp_ieee_overflow 0
		.amdhsa_exception_fp_ieee_underflow 0
		.amdhsa_exception_fp_ieee_inexact 0
		.amdhsa_exception_int_div_zero 0
	.end_amdhsa_kernel

amdhsa.kernels:
  - .agpr_count:     0
    .args:
      - .offset:         0
        .size:           272
        .value_kind:     by_value
      - .offset:         272
        .size:           4
        .value_kind:     hidden_block_count_x
      - .offset:         276
        .size:           4
        .value_kind:     hidden_block_count_y
      - .offset:         280
        .size:           4
        .value_kind:     hidden_block_count_z
      - .offset:         284
        .size:           2
        .value_kind:     hidden_group_size_x
      - .offset:         286
        .size:           2
        .value_kind:     hidden_group_size_y
      - .offset:         288
        .size:           2
        .value_kind:     hidden_group_size_z
      - .offset:         290
        .size:           2
        .value_kind:     hidden_remainder_x
      - .offset:         292
        .size:           2
        .value_kind:     hidden_remainder_y
      - .offset:         294
        .size:           2
        .value_kind:     hidden_remainder_z
      - .offset:         312
        .size:           8
        .value_kind:     hidden_global_offset_x
      - .offset:         320
        .size:           8
        .value_kind:     hidden_global_offset_y
      - .offset:         328
        .size:           8
        .value_kind:     hidden_global_offset_z
      - .offset:         336
        .size:           2
        .value_kind:     hidden_grid_dims
      - .offset:         392
        .size:           4
        .value_kind:     hidden_dynamic_lds_size
    .group_segment_fixed_size: 0
    .kernarg_segment_align: 8
    .kernarg_segment_size: 528
    .language:       OpenCL C
    .language_version:
      - 2
      - 0
    .max_flat_workgroup_size: 512
    .name:           _Z9hymba_fwd4Args
    .private_segment_fixed_size: 0
    .sgpr_count:     108
    .sgpr_spill_count: 449
    .symbol:         _Z9hymba_fwd4Args.kd
    .uniform_work_group_size: 1
    .uses_dynamic_stack: false
    .vgpr_count:     256
    .vgpr_spill_count: 0
    .wavefront_size: 64
